# b2-tail slice of the idle-workgroup cache copy moved from P1's last round (copy outlasted the tail units) to P8's last round (workgroups idle there)
# speedup vs baseline: 1.0241x; 1.0027x over previous
; #define TID_NOW(wave_sg) tid_now_(wave_sg)
; __device__ __forceinline__ void idle_copy(KParams P, int nwg, unsigned lo, unsigned hi, const int wave_sg) {
;     const int G = gridDim.x, busy = nwg % G; const int tid = TID_NOW(wave_sg);
;     if (busy == 0 || (int)blockIdx.x < busy) { if (busy == 0) copy_slice(P, lo, hi, blockIdx.x * 512 + tid, G * 512); return; }
;     copy_slice(P, lo, hi, (blockIdx.x - busy) * 512 + tid, (G - busy) * 512);
; __global__ void __launch_bounds__(512, 2) mega_fwd(Params Parg) {
;     ...
;       if (bgr) { idle_copy(P, 129 * 22, 0u, CP_S1, wave_sg); idle_copy(P, 129 * 22, CP_S1 + B2_C1, CP_S2, wave_sg); } }
.LBB0_284:
	s_andn2_b64 vcc, exec, s[0:1]
	v_mbcnt_lo_u32_b32 v0, -1, 0
	v_mbcnt_hi_u32_b32 v0, -1, v0
	v_lshl_or_b32 v0, s96, 6, v0
	s_branch .LBB0_293

; #define TID_NOW(wave_sg) tid_now_(wave_sg)
; template <int L, int R> __device__ __forceinline__ void copy_seg(const float* __restrict__ src, float* __restrict__ dst, unsigned lo, unsigned hi, unsigned t0, unsigned nthr) {
;     constexpr unsigned PER = (unsigned)(L - 1) * R / 4, LR4 = (unsigned)L * R / 4, R4 = R / 4;
;     const f32x4* s4 = (const f32x4*)src; f32x4* d4 = (f32x4*)dst;
;     unsigned i = lo + t0;
;     for (; i + 3 * nthr < hi; i += 4 * nthr) {
; __device__ __forceinline__ void idle_copy(KParams P, int nwg, unsigned lo, unsigned hi, const int wave_sg) {
;     const int G = gridDim.x, busy = nwg % G; const int tid = TID_NOW(wave_sg);
;     if (busy == 0 || (int)blockIdx.x < busy) { if (busy == 0) copy_slice(P, lo, hi, blockIdx.x * 512 + tid, G * 512); return; }
;     copy_slice(P, lo, hi, (blockIdx.x - busy) * 512 + tid, (G - busy) * 512);
.LBB0_1206:
	v_readlane_b32 s0, v255, 18
	v_readlane_b32 s1, v255, 19
	s_cmp_gt_i32 s2, 21
	s_cbranch_scc0 .Lmvb2_done
	s_and_b64 vcc, exec, s[0:1]
	s_cbranch_vccnz .Lmvb2_done
	v_mbcnt_lo_u32_b32 v0, -1, 0
	v_mbcnt_hi_u32_b32 v0, -1, v0
	v_lshl_or_b32 v0, s96, 6, v0
	v_readlane_b32 s6, v255, 2
	v_readlane_b32 s7, v255, 3
	s_nop 0
	s_load_dwordx2 s[8:9], s[6:7], 0xc0
	s_waitcnt lgkmcnt(0)
	s_lshl_b32 s3, s2, 9
	s_load_dwordx2 s[0:1], s[6:7], 0x20
	s_waitcnt lgkmcnt(0)
	s_add_u32 s4, s8, 0x10680000
	s_addc_u32 s5, s9, 0
	s_add_i32 s3, s3, 0x57d400
	v_add_u32_e32 v2, s3, v0
	v_add_u32_e32 v0, 0x57c00, v2
	s_mov_b32 s3, 0x7fc000
	v_cmp_gt_u32_e32 vcc, s3, v0
	s_and_saveexec_b64 s[6:7], vcc
	s_cbranch_execz .Lmvb2_289
	s_mov_b64 s[8:9], 0
	s_mov_b32 s3, 0x2010081
	s_mov_b32 s10, 0xffff0080
	v_mov_b32_e32 v1, 0
	s_mov_b32 s11, 0x7fbfff

; #define TID_NOW(wave_sg) tid_now_(wave_sg)
; __device__ __forceinline__ unsigned xb_ld(unsigned* p)              { return __hip_atomic_load(p, __ATOMIC_RELAXED, __HIP_MEMORY_SCOPE_AGENT); }
; __device__ __forceinline__ void xcd_barrier_complete(unsigned* bar, unsigned x, unsigned& nloc, unsigned& nx) {
;     const unsigned G = gridDim.x * gridDim.y * gridDim.z;
;     unsigned sum, cnt, mine, sp = 0u;
;     for (;;) {
;         sum = 0u; cnt = 0u; mine = 0u;
; #pragma unroll
;         for (unsigned j = 0; j < 16; ++j) { const unsigned c = xb_ld(&bar[XB_XCNT(j)]); sum += c; cnt += (c > 0u) ? 1u : 0u; mine = (j == x) ? c : mine; }
; __device__ __forceinline__ void xcd_barrier(const XcdBarrier& b, int wave_sg) {
;     asm volatile("s_waitcnt vmcnt(0)" ::: "memory");
;     __syncthreads();
;     if (TID_NOW(wave_sg) == 0) {
;         unsigned* bar = b.bar;
;         __builtin_amdgcn_s_waitcnt(0);
;         unsigned nloc = b.st[0], nx = b.st[1];
;         if (nloc == 0u) { xcd_barrier_complete(bar, b.x, nloc, nx); b.st[0] = nloc; b.st[1] = nx; }
.Lmvb2_292:
	s_or_b64 exec, exec, s[6:7]
.Lmvb2_done:
	s_waitcnt vmcnt(0)
	s_barrier
	v_mbcnt_lo_u32_b32 v0, -1, 0
	v_mbcnt_hi_u32_b32 v0, -1, v0
	v_lshl_or_b32 v0, s96, 6, v0
	s_nop 0
	v_cmp_eq_u32_e32 vcc, 0, v0
	s_and_saveexec_b64 s[0:1], vcc
	s_cbranch_execz .LBB0_1258
	s_add_i32 s3, 0, 0x25ff0
	v_mov_b32_e32 v0, s3
	s_waitcnt vmcnt(0) expcnt(0) lgkmcnt(0)
	ds_read_b32 v2, v0
	s_add_i32 s3, 0, 0x25ff4
	v_mov_b32_e32 v0, s3
	ds_read_b32 v0, v0
	s_waitcnt lgkmcnt(1)
	v_cmp_ne_u32_e32 vcc, 0, v2
	s_cbranch_vccnz .LBB0_1222
	v_readlane_b32 s6, v255, 2
	v_readlane_b32 s7, v255, 3
	s_load_dwordx2 s[4:5], s[6:7], 0xd0
	v_readlane_b32 s3, v255, 4
	v_readlane_b32 s38, v255, 5
	v_readlane_b32 s39, v255, 6
	s_mov_b32 s33, 1
	s_waitcnt lgkmcnt(0)
	s_mul_i32 s3, s5, s3
	s_mul_i32 s3, s3, s4
	s_add_u32 s4, s38, 0x49800200
	s_addc_u32 s5, s39, 0
	s_add_u32 s6, s38, 0x49800400
	s_addc_u32 s7, s39, 0
	s_add_u32 s8, s38, 0x49800500
	s_addc_u32 s9, s39, 0
	s_add_u32 s10, s38, 0x49800600
	s_addc_u32 s11, s39, 0
	s_add_u32 s12, s38, 0x49800700
	s_addc_u32 s13, s39, 0
	s_add_u32 s14, s38, 0x49800800
	s_addc_u32 s15, s39, 0
	s_add_u32 s16, s38, 0x49800900
	s_addc_u32 s17, s39, 0
	s_add_u32 s18, s38, 0x49800a00
	s_addc_u32 s19, s39, 0
	s_add_u32 s20, s38, 0x49800b00
	s_addc_u32 s21, s39, 0
	s_add_u32 s22, s38, 0x49800c00
	s_addc_u32 s23, s39, 0
	s_add_u32 s24, s38, 0x49800d00
	s_addc_u32 s25, s39, 0
	s_add_u32 s26, s38, 0x49800e00
	s_addc_u32 s27, s39, 0
	s_add_u32 s28, s38, 0x49800f00
	s_addc_u32 s29, s39, 0
	s_add_u32 s30, s38, 0x49801000
	s_addc_u32 s31, s39, 0
	s_add_u32 s34, s38, 0x49801100
	s_addc_u32 s35, s39, 0
	s_add_u32 s36, s38, 0x49801200
	s_addc_u32 s37, s39, 0
	s_add_u32 s38, s38, 0x49801300
	s_addc_u32 s39, s39, 0
	v_mov_b32_e32 v16, 0
	s_branch .LBB0_1210
